# hgrn_a hgrn_read chain: the 16 steps' LDS read pairs batched (2 batches of 8 steps into free temporaries, one lgkmcnt(0) each) instead of a wait per step
# baseline (speedup 1.0000x reference)
; #define LAS __attribute__((address_space(3)))
; __device__ __forceinline__ unsigned pk2(float lo, float hi) { return f2bf(lo) | (f2bf(hi) << 16); }
; __device__ __forceinline__ float bflo(unsigned w) { return __uint_as_float(w << 16); }
; __device__ __forceinline__ float bfhi(unsigned w) { return __uint_as_float(w & 0xffff0000u); }
; __device__ __forceinline__ void stage_gates(const uint4 raw, const float4 lb0, const float4 lb1, LAS float* Gs, LAS u16* KKs, int t, int c8) {
;     const unsigned w[4] = {raw.x, raw.y, raw.z, raw.w}; const float lb[8] = {lb0.x, lb0.y, lb0.z, lb0.w, lb1.x, lb1.y, lb1.z, lb1.w};
;     float g[8], kk[8];
; #pragma unroll
;     for (int e = 0; e < 8; ++e) { const float a = (e & 1) ? bfhi(w[e >> 1]) : bflo(w[e >> 1]);
;         const float sig = __builtin_amdgcn_rcpf(1.f + __expf(-a)); const float f = lb[e] + (1.f - lb[e]) * sig;
;         g[e] = fmaxf(__logf(f), -80.f); kk[e] = (1.f - lb[e]) * (1.f - sig); }
;     *(LAS f4v*)(Gs + t * 128 + c8) = (f4v){g[0], g[1], g[2], g[3]}; *(LAS f4v*)(Gs + t * 128 + c8 + 4) = (f4v){g[4], g[5], g[6], g[7]};
;     *(LAS u4v*)(KKs + t * 128 + c8) = (u4v){pk2(kk[0], kk[1]), pk2(kk[2], kk[3]), pk2(kk[4], kk[5]), pk2(kk[6], kk[7])};
; }
; __device__ __forceinline__ void hgrn_a_item(const u16* P, const float* LBl0, const float* LBl1, float* ST, float* DT, int rc, int h, LAS unsigned char* L, int tid) {
;     ...
;         for (int i = 0; i < 2; ++i) { const int idx = tid + 512 * i; stage_gates(dir ? rab[i] : raf[i], dir ? lbb[i][0] : lbf[i][0], dir ? lbb[i][1] : lbf[i][1], Gs, KKs, idx >> 4, (idx & 15) * 8); }
.LBB0_343:
	v_cndmask_b32_e64 v0, v44, v40, s[54:55]
	v_lshlrev_b32_e32 v11, 16, v0
	v_and_b32_e32 v0, 0xffff0000, v0
	v_mul_f32_e32 v0, 0xbfb8aa3b, v0
	v_exp_f32_e32 v0, v0
	v_cndmask_b32_e64 v1, v45, v41, s[54:55]
	v_mul_f32_e32 v11, 0xbfb8aa3b, v11
	v_exp_f32_e32 v11, v11
	v_add_f32_e32 v0, 1.0, v0
	v_rcp_f32_e32 v24, v0
	v_lshlrev_b32_e32 v0, 16, v1
	v_mul_f32_e32 v0, 0xbfb8aa3b, v0
	v_exp_f32_e32 v0, v0
	v_cndmask_b32_e64 v8, v46, v42, s[54:55]
	v_cndmask_b32_e64 v9, v47, v43, s[54:55]
	v_add_f32_e32 v11, 1.0, v11
	v_add_f32_e32 v0, 1.0, v0
	v_rcp_f32_e32 v17, v0
	v_and_b32_e32 v0, 0xffff0000, v1
	v_mul_f32_e32 v0, 0xbfb8aa3b, v0
	v_exp_f32_e32 v0, v0
	v_lshlrev_b32_e32 v1, 16, v9
	v_mul_f32_e32 v1, 0xbfb8aa3b, v1
	v_exp_f32_e32 v1, v1
	v_add_f32_e32 v0, 1.0, v0
	v_rcp_f32_e32 v25, v0
	v_lshlrev_b32_e32 v0, 16, v8
	v_mul_f32_e32 v0, 0xbfb8aa3b, v0
	v_exp_f32_e32 v0, v0
	v_rcp_f32_e32 v16, v11
	v_cndmask_b32_e64 v13, v39, v37, s[54:55]
	v_cndmask_b32_e64 v12, v60, v36, s[54:55]
	v_and_b32_e32 v10, 0xffff0000, v9
	v_add_f32_e32 v0, 1.0, v0
	v_add_f32_e32 v1, 1.0, v1
	v_cndmask_b32_e64 v3, v61, v65, s[54:55]
	v_cndmask_b32_e64 v2, v120, v118, s[54:55]
	v_rcp_f32_e32 v22, v0
	v_and_b32_e32 v0, 0xffff0000, v8
	v_rcp_f32_e32 v23, v1
	v_mul_f32_e32 v1, 0xbfb8aa3b, v10
	v_pk_add_f32 v[8:9], v[12:13], 1.0 op_sel_hi:[1,0] neg_lo:[1,0] neg_hi:[1,0]
	v_pk_add_f32 v[10:11], v[16:17], 1.0 op_sel_hi:[1,0] neg_lo:[1,0] neg_hi:[1,0]
	v_pk_add_f32 v[14:15], v[24:25], 1.0 op_sel_hi:[1,0] neg_lo:[1,0] neg_hi:[1,0]
	v_pk_mul_f32 v[18:19], v[8:9], v[10:11]
	v_pk_add_f32 v[10:11], v[2:3], 1.0 op_sel_hi:[1,0] neg_lo:[1,0] neg_hi:[1,0]
	v_cndmask_b32_e64 v7, v35, v33, s[54:55]
	v_pk_mul_f32 v[20:21], v[10:11], v[14:15]
	v_fma_f32 v14, v8, v16, v12
	v_cmp_gt_f32_e32 vcc, s91, v14
	v_cndmask_b32_e64 v6, v56, v32, s[54:55]
	v_mul_f32_e32 v0, 0xbfb8aa3b, v0
	v_cndmask_b32_e64 v15, 0, 32, vcc
	v_ldexp_f32 v14, v14, v15
	v_log_f32_e32 v14, v14
	v_exp_f32_e32 v0, v0
	v_cndmask_b32_e64 v5, v57, v63, s[54:55]
	v_cndmask_b32_e64 v4, v62, v38, s[54:55]
	v_mul_f32_e32 v15, 0x3f317217, v14
	v_fma_f32 v15, v14, s27, -v15
	v_fmac_f32_e32 v15, 0x3377d1cf, v14
	v_fmac_f32_e32 v15, 0x3f317217, v14
	v_cmp_lt_f32_e64 s[0:1], |v14|, s73
	v_add_f32_e32 v0, 1.0, v0
	v_rcp_f32_e32 v0, v0
	v_cndmask_b32_e64 v14, v14, v15, s[0:1]
	v_cndmask_b32_e32 v15, 0, v183, vcc
	v_sub_f32_e32 v14, v14, v15
	v_fma_f32 v15, v10, v24, v2
	v_cmp_gt_f32_e32 vcc, s91, v15
	v_max_f32_e32 v14, 0xc2a00000, v14
	v_exp_f32_e32 v1, v1
	v_cndmask_b32_e64 v16, 0, 32, vcc
	v_ldexp_f32 v15, v15, v16
	v_log_f32_e32 v15, v15
	v_add_f32_e32 v1, 1.0, v1
	v_rcp_f32_e32 v1, v1
	v_mul_f32_e32 v16, 0x3f317217, v15
	v_fma_f32 v16, v15, s27, -v16
	v_fmac_f32_e32 v16, 0x3377d1cf, v15
	v_fmac_f32_e32 v16, 0x3f317217, v15
	v_cmp_lt_f32_e64 s[0:1], |v15|, s73
	s_nop 1
	v_cndmask_b32_e64 v15, v15, v16, s[0:1]
	v_cndmask_b32_e32 v16, 0, v183, vcc
	v_sub_f32_e32 v15, v15, v16
	v_fma_f32 v16, v9, v17, v13
	v_cmp_gt_f32_e32 vcc, s91, v16
	v_max_f32_e32 v15, 0xc2a00000, v15
	s_nop 0
	v_cndmask_b32_e64 v17, 0, 32, vcc
	v_ldexp_f32 v16, v16, v17
	v_log_f32_e32 v16, v16
	s_nop 0
	v_mul_f32_e32 v17, 0x3f317217, v16
	v_fma_f32 v17, v16, s27, -v17
	v_fmac_f32_e32 v17, 0x3377d1cf, v16
	v_fmac_f32_e32 v17, 0x3f317217, v16
	v_cmp_lt_f32_e64 s[0:1], |v16|, s73
	s_nop 1
	v_cndmask_b32_e64 v16, v16, v17, s[0:1]
	v_cndmask_b32_e32 v17, 0, v183, vcc
	v_sub_f32_e32 v16, v16, v17
	v_fma_f32 v17, v11, v25, v3
	v_cmp_gt_f32_e32 vcc, s91, v17
	v_max_f32_e32 v16, 0xc2a00000, v16
	s_nop 0
	v_cndmask_b32_e64 v24, 0, 32, vcc
	v_ldexp_f32 v17, v17, v24
	v_log_f32_e32 v17, v17
	s_nop 0
	v_mul_f32_e32 v24, 0x3f317217, v17
	v_fma_f32 v24, v17, s27, -v24
	v_fmac_f32_e32 v24, 0x3377d1cf, v17
	v_fmac_f32_e32 v24, 0x3f317217, v17
	v_cmp_lt_f32_e64 s[0:1], |v17|, s73
	s_nop 1
	v_cndmask_b32_e64 v17, v17, v24, s[0:1]
	v_cndmask_b32_e32 v24, 0, v183, vcc
	v_sub_f32_e32 v17, v17, v24
	v_max_f32_e32 v17, 0xc2a00000, v17
	ds_write_b128 v141, v[14:17] offset:40960
	v_pk_add_f32 v[14:15], v[6:7], 1.0 op_sel_hi:[1,0] neg_lo:[1,0] neg_hi:[1,0]
	v_pk_add_f32 v[16:17], v[22:23], 1.0 op_sel_hi:[1,0] neg_lo:[1,0] neg_hi:[1,0]
	s_nop 0
	v_pk_mul_f32 v[28:29], v[14:15], v[16:17]
	v_fma_f32 v16, v14, v22, v6
	v_cmp_gt_f32_e32 vcc, s91, v16
	s_nop 1
	v_cndmask_b32_e64 v17, 0, 32, vcc
	v_ldexp_f32 v16, v16, v17
	v_log_f32_e32 v16, v16
	s_nop 0
	v_mul_f32_e32 v17, 0x3f317217, v16
	v_fma_f32 v17, v16, s27, -v17
	v_fmac_f32_e32 v17, 0x3377d1cf, v16
	v_fmac_f32_e32 v17, 0x3f317217, v16
	v_cmp_lt_f32_e64 s[0:1], |v16|, s73
	s_nop 1
	v_cndmask_b32_e64 v16, v16, v17, s[0:1]
	v_cndmask_b32_e32 v17, 0, v183, vcc
	v_sub_f32_e32 v16, v16, v17
	v_max_f32_e32 v24, 0xc2a00000, v16
	v_pk_add_f32 v[16:17], v[4:5], 1.0 op_sel_hi:[1,0] neg_lo:[1,0] neg_hi:[1,0]
	s_nop 0
	v_fma_f32 v22, v16, v0, v4
	v_cmp_gt_f32_e32 vcc, s91, v22
	s_nop 1
	v_cndmask_b32_e64 v25, 0, 32, vcc
	v_ldexp_f32 v22, v22, v25
	v_log_f32_e32 v22, v22
	s_nop 0
	v_mul_f32_e32 v25, 0x3f317217, v22
	v_fma_f32 v25, v22, s27, -v25
	v_fmac_f32_e32 v25, 0x3377d1cf, v22
	v_fmac_f32_e32 v25, 0x3f317217, v22
	v_cmp_lt_f32_e64 s[0:1], |v22|, s73
	s_nop 1
	v_cndmask_b32_e64 v22, v22, v25, s[0:1]
	v_cndmask_b32_e32 v25, 0, v183, vcc
	v_sub_f32_e32 v22, v22, v25
	v_max_f32_e32 v25, 0xc2a00000, v22
	v_fma_f32 v22, v15, v23, v7
	v_cmp_gt_f32_e32 vcc, s91, v22
	s_nop 1
	v_cndmask_b32_e64 v23, 0, 32, vcc
	v_ldexp_f32 v22, v22, v23
	v_log_f32_e32 v22, v22
	s_nop 0
	v_mul_f32_e32 v23, 0x3f317217, v22
	v_fma_f32 v23, v22, s27, -v23
	v_fmac_f32_e32 v23, 0x3377d1cf, v22
	v_fmac_f32_e32 v23, 0x3f317217, v22
	v_cmp_lt_f32_e64 s[0:1], |v22|, s73
; #define LAS __attribute__((address_space(3)))
; __device__ __forceinline__ unsigned pk2(float lo, float hi) { return f2bf(lo) | (f2bf(hi) << 16); }
; __device__ __forceinline__ float bflo(unsigned w) { return __uint_as_float(w << 16); }
; __device__ __forceinline__ float bfhi(unsigned w) { return __uint_as_float(w & 0xffff0000u); }
; __device__ __forceinline__ void stage_gates(const uint4 raw, const float4 lb0, const float4 lb1, LAS float* Gs, LAS u16* KKs, int t, int c8) {
;     const unsigned w[4] = {raw.x, raw.y, raw.z, raw.w}; const float lb[8] = {lb0.x, lb0.y, lb0.z, lb0.w, lb1.x, lb1.y, lb1.z, lb1.w};
;     float g[8], kk[8];
; #pragma unroll
;     for (int e = 0; e < 8; ++e) { const float a = (e & 1) ? bfhi(w[e >> 1]) : bflo(w[e >> 1]);
;         const float sig = __builtin_amdgcn_rcpf(1.f + __expf(-a)); const float f = lb[e] + (1.f - lb[e]) * sig;
;         g[e] = fmaxf(__logf(f), -80.f); kk[e] = (1.f - lb[e]) * (1.f - sig); }
;     *(LAS f4v*)(Gs + t * 128 + c8) = (f4v){g[0], g[1], g[2], g[3]}; *(LAS f4v*)(Gs + t * 128 + c8 + 4) = (f4v){g[4], g[5], g[6], g[7]};
;     *(LAS u4v*)(KKs + t * 128 + c8) = (u4v){pk2(kk[0], kk[1]), pk2(kk[2], kk[3]), pk2(kk[4], kk[5]), pk2(kk[6], kk[7])};
; }
; __device__ __forceinline__ void hgrn_a_item(const u16* P, const float* LBl0, const float* LBl1, float* ST, float* DT, int rc, int h, LAS unsigned char* L, int tid) {
;     ...
;         for (int i = 0; i < 2; ++i) { const int idx = tid + 512 * i; stage_gates(dir ? rab[i] : raf[i], dir ? lbb[i][0] : lbf[i][0], dir ? lbb[i][1] : lbf[i][1], Gs, KKs, idx >> 4, (idx & 15) * 8); }
	s_nop 1
	v_cndmask_b32_e64 v22, v22, v23, s[0:1]
	v_cndmask_b32_e32 v23, 0, v183, vcc
	v_sub_f32_e32 v22, v22, v23
	v_max_f32_e32 v26, 0xc2a00000, v22
	v_fma_f32 v22, v17, v1, v5
	v_cmp_gt_f32_e32 vcc, s91, v22
	v_pk_add_f32 v[0:1], v[0:1], 1.0 op_sel_hi:[1,0] neg_lo:[1,0] neg_hi:[1,0]
	s_nop 0
	v_cndmask_b32_e64 v23, 0, 32, vcc
	v_ldexp_f32 v22, v22, v23
	v_log_f32_e32 v22, v22
	v_pk_mul_f32 v[0:1], v[16:17], v[0:1]
	v_mul_f32_e32 v23, 0x3f317217, v22
	v_fma_f32 v23, v22, s27, -v23
	v_fmac_f32_e32 v23, 0x3377d1cf, v22
	v_fmac_f32_e32 v23, 0x3f317217, v22
	v_cmp_lt_f32_e64 s[0:1], |v22|, s73
	s_nop 1
	v_cndmask_b32_e64 v22, v22, v23, s[0:1]
	v_cndmask_b32_e32 v23, 0, v183, vcc
	v_sub_f32_e32 v22, v22, v23
	v_max_f32_e32 v27, 0xc2a00000, v22
	ds_write_b128 v141, v[24:27] offset:40976
	v_bfe_u32 v22, v1, 16, 1
	v_bfe_u32 v23, v0, 16, 1
	v_bfe_u32 v24, v21, 16, 1
	v_bfe_u32 v25, v20, 16, 1
	v_add3_u32 v25, v20, v25, s3
	v_add3_u32 v24, v21, v24, s3
	v_add3_u32 v0, v0, v23, s3
	v_add3_u32 v1, v1, v22, s3
	v_bfe_u32 v20, v18, 16, 1
	v_bfe_u32 v21, v19, 16, 1
	v_bfe_u32 v22, v28, 16, 1
	v_bfe_u32 v23, v29, 16, 1
	v_add3_u32 v23, v29, v23, s3
	v_add3_u32 v22, v28, v22, s3
	v_add3_u32 v19, v19, v21, s3
	v_add3_u32 v18, v18, v20, s3
	v_lshrrev_b32_e32 v18, 16, v18
	v_lshrrev_b32_e32 v19, 16, v19
	v_lshrrev_b32_e32 v20, 16, v22
	v_lshrrev_b32_e32 v21, 16, v23
	v_and_or_b32 v21, v1, s71, v21
	v_and_or_b32 v20, v0, s71, v20
	v_and_or_b32 v19, v24, s71, v19
	v_and_or_b32 v18, v25, s71, v18
	v_cndmask_b32_e64 v0, v52, v48, s[54:55]
	ds_write_b128 v164, v[18:21]
	v_lshlrev_b32_e32 v18, 16, v0
	v_and_b32_e32 v0, 0xffff0000, v0
	v_mul_f32_e32 v0, 0xbfb8aa3b, v0
	v_exp_f32_e32 v0, v0
	v_cndmask_b32_e64 v1, v53, v49, s[54:55]
	v_cndmask_b32_e64 v23, v54, v50, s[54:55]
	v_mul_f32_e32 v18, 0xbfb8aa3b, v18
	v_add_f32_e32 v0, 1.0, v0
	v_rcp_f32_e32 v20, v0
	v_lshlrev_b32_e32 v0, 16, v1
	v_mul_f32_e32 v0, 0xbfb8aa3b, v0
	v_exp_f32_e32 v0, v0
	v_exp_f32_e32 v18, v18
	v_cndmask_b32_e64 v25, v55, v51, s[54:55]
	v_fmac_f32_e32 v2, v10, v20
	v_add_f32_e32 v0, 1.0, v0
	v_rcp_f32_e32 v19, v0
	v_and_b32_e32 v0, 0xffff0000, v1
	v_mul_f32_e32 v0, 0xbfb8aa3b, v0
	v_exp_f32_e32 v0, v0
	v_add_f32_e32 v18, 1.0, v18
	v_rcp_f32_e32 v18, v18
	v_fmac_f32_e32 v13, v9, v19
	v_add_f32_e32 v0, 1.0, v0
	v_rcp_f32_e32 v21, v0
	v_lshlrev_b32_e32 v0, 16, v23
	v_mul_f32_e32 v0, 0xbfb8aa3b, v0
	v_exp_f32_e32 v0, v0
	v_fmac_f32_e32 v12, v8, v18
	v_cmp_gt_f32_e32 vcc, s91, v12
	v_fmac_f32_e32 v3, v11, v21
	v_add_f32_e32 v0, 1.0, v0
	v_rcp_f32_e32 v22, v0
	v_and_b32_e32 v0, 0xffff0000, v23
	v_mul_f32_e32 v0, 0xbfb8aa3b, v0
	v_exp_f32_e32 v0, v0
	v_fmac_f32_e32 v6, v14, v22
	v_and_b32_e32 v29, 0xffff0000, v25
	v_add_f32_e32 v0, 1.0, v0
	v_rcp_f32_e32 v24, v0
	v_lshlrev_b32_e32 v0, 16, v25
	v_mul_f32_e32 v0, 0xbfb8aa3b, v0
	v_exp_f32_e32 v0, v0
	v_fmac_f32_e32 v4, v16, v24
	v_add_f32_e32 v0, 1.0, v0
	v_rcp_f32_e32 v23, v0
	v_cndmask_b32_e64 v0, 0, 32, vcc
	v_ldexp_f32 v0, v12, v0
	v_log_f32_e32 v0, v0
	v_fmac_f32_e32 v7, v15, v23
	v_mul_f32_e32 v1, 0x3f317217, v0
	v_fma_f32 v1, v0, s27, -v1
	v_fmac_f32_e32 v1, 0x3377d1cf, v0
	v_fmac_f32_e32 v1, 0x3f317217, v0
	v_cmp_lt_f32_e64 s[0:1], |v0|, s73
	s_nop 1
	v_cndmask_b32_e64 v0, v0, v1, s[0:1]
	v_cndmask_b32_e32 v1, 0, v183, vcc
	v_cmp_gt_f32_e32 vcc, s91, v2
	v_sub_f32_e32 v0, v0, v1
	v_max_f32_e32 v0, 0xc2a00000, v0
	v_cndmask_b32_e64 v1, 0, 32, vcc
	v_ldexp_f32 v1, v2, v1
	v_log_f32_e32 v1, v1
	s_nop 0
	v_mul_f32_e32 v2, 0x3f317217, v1
	v_fma_f32 v2, v1, s27, -v2
	v_fmac_f32_e32 v2, 0x3377d1cf, v1
	v_fmac_f32_e32 v2, 0x3f317217, v1
	v_cmp_lt_f32_e64 s[0:1], |v1|, s73
	s_nop 1
	v_cndmask_b32_e64 v1, v1, v2, s[0:1]
	v_cndmask_b32_e32 v2, 0, v183, vcc
	v_cmp_gt_f32_e32 vcc, s91, v13
	v_sub_f32_e32 v1, v1, v2
	v_max_f32_e32 v1, 0xc2a00000, v1
	v_cndmask_b32_e64 v2, 0, 32, vcc
	v_ldexp_f32 v2, v13, v2
	v_log_f32_e32 v2, v2
	v_cndmask_b32_e64 v13, v153, v130, s[54:55]
	v_mul_f32_e32 v12, 0x3f317217, v2
	v_fma_f32 v12, v2, s27, -v12
	v_fmac_f32_e32 v12, 0x3377d1cf, v2
	v_fmac_f32_e32 v12, 0x3f317217, v2
	v_cmp_lt_f32_e64 s[0:1], |v2|, s73
	s_nop 1
	v_cndmask_b32_e64 v2, v2, v12, s[0:1]
	v_cndmask_b32_e32 v12, 0, v183, vcc
	v_cmp_gt_f32_e32 vcc, s91, v3
	v_sub_f32_e32 v2, v2, v12
	v_max_f32_e32 v2, 0xc2a00000, v2
	v_cndmask_b32_e64 v12, 0, 32, vcc
	v_ldexp_f32 v3, v3, v12
	v_log_f32_e32 v3, v3
	s_nop 0
	v_mul_f32_e32 v12, 0x3f317217, v3
	v_fma_f32 v12, v3, s27, -v12
	v_fmac_f32_e32 v12, 0x3377d1cf, v3
	v_fmac_f32_e32 v12, 0x3f317217, v3
	v_cmp_lt_f32_e64 s[0:1], |v3|, s73
	s_nop 1
	v_cndmask_b32_e64 v3, v3, v12, s[0:1]
	v_cndmask_b32_e32 v12, 0, v183, vcc
	v_cmp_gt_f32_e32 vcc, s91, v6
	v_sub_f32_e32 v3, v3, v12
	v_max_f32_e32 v3, 0xc2a00000, v3
	v_cndmask_b32_e64 v12, 0, 32, vcc
	v_ldexp_f32 v6, v6, v12
	v_log_f32_e32 v6, v6
	s_nop 0
	v_mul_f32_e32 v12, 0x3f317217, v6
	v_fma_f32 v12, v6, s27, -v12
	v_fmac_f32_e32 v12, 0x3377d1cf, v6
	v_fmac_f32_e32 v12, 0x3f317217, v6
	v_cmp_lt_f32_e64 s[0:1], |v6|, s73
	s_nop 1
	v_cndmask_b32_e64 v6, v6, v12, s[0:1]
	v_cndmask_b32_e32 v12, 0, v183, vcc
	v_sub_f32_e32 v6, v6, v12
	v_cmp_gt_f32_e32 vcc, s91, v4
	v_max_f32_e32 v26, 0xc2a00000, v6
	s_nop 0
	v_cndmask_b32_e64 v6, 0, 32, vcc
	v_ldexp_f32 v4, v4, v6
	v_log_f32_e32 v4, v4
	s_nop 0
	v_mul_f32_e32 v6, 0x3f317217, v4
	v_fma_f32 v6, v4, s27, -v6
	v_fmac_f32_e32 v6, 0x3377d1cf, v4
	v_fmac_f32_e32 v6, 0x3f317217, v4
	v_cmp_lt_f32_e64 s[0:1], |v4|, s73
	s_nop 1
	v_cndmask_b32_e64 v4, v4, v6, s[0:1]
	v_cndmask_b32_e32 v6, 0, v183, vcc
	v_sub_f32_e32 v4, v4, v6
	v_cmp_gt_f32_e32 vcc, s91, v7
	v_max_f32_e32 v27, 0xc2a00000, v4
	s_nop 0
	v_cndmask_b32_e64 v4, 0, 32, vcc
; #define LAS __attribute__((address_space(3)))
; __device__ __forceinline__ float bf2f(unsigned h) { return __uint_as_float(h << 16); }
; __device__ __forceinline__ void hgrn_read(HgrnT& G, const LAS float* Gs, const LAS u16* KKs, int dir, int k, int Is, LAS float* tot) {
;     float run = 0.f;
; #pragma unroll
;     for (int js = 0; js < 16; ++js) { const int t = dir ? 63 - (16 * Is + js) : 16 * Is + js;
;         run += Gs[t * 128 + k]; G.bl[js] = run; G.kk[js] = bf2f(KKs[t * 128 + k]); }
;     tot[Is * 128 + k] = run;
; }
	v_ldexp_f32 v4, v7, v4
	v_log_f32_e32 v4, v4
	s_nop 0
	v_mul_f32_e32 v6, 0x3f317217, v4
	v_fma_f32 v6, v4, s27, -v6
	v_fmac_f32_e32 v6, 0x3377d1cf, v4
	v_fmac_f32_e32 v6, 0x3f317217, v4
	v_cmp_lt_f32_e64 s[0:1], |v4|, s73
	s_nop 1
	v_cndmask_b32_e64 v4, v4, v6, s[0:1]
	v_cndmask_b32_e32 v6, 0, v183, vcc
	v_sub_f32_e32 v4, v4, v6
	v_max_f32_e32 v28, 0xc2a00000, v4
	v_mul_f32_e32 v4, 0xbfb8aa3b, v29
	v_exp_f32_e32 v4, v4
	s_nop 0
	v_add_f32_e32 v4, 1.0, v4
	v_rcp_f32_e32 v25, v4
	s_nop 0
	v_fmac_f32_e32 v5, v17, v25
	v_cmp_gt_f32_e32 vcc, s91, v5
	v_pk_add_f32 v[6:7], v[24:25], 1.0 op_sel_hi:[1,0] neg_lo:[1,0] neg_hi:[1,0]
	s_nop 0
	v_cndmask_b32_e64 v4, 0, 32, vcc
	v_ldexp_f32 v4, v5, v4
	v_log_f32_e32 v4, v4
	v_pk_mul_f32 v[6:7], v[16:17], v[6:7]
	v_mul_f32_e32 v5, 0x3f317217, v4
	v_fma_f32 v5, v4, s27, -v5
	v_fmac_f32_e32 v5, 0x3377d1cf, v4
	v_fmac_f32_e32 v5, 0x3f317217, v4
	v_cmp_lt_f32_e64 s[0:1], |v4|, s73
	s_nop 1
	v_cndmask_b32_e64 v4, v4, v5, s[0:1]
	v_cndmask_b32_e32 v5, 0, v183, vcc
	v_sub_f32_e32 v4, v4, v5
	v_max_f32_e32 v29, 0xc2a00000, v4
	ds_write_b128 v141, v[0:3] offset:57344
	ds_write_b128 v141, v[26:29] offset:57360
	v_pk_add_f32 v[2:3], v[20:21], 1.0 op_sel_hi:[1,0] neg_lo:[1,0] neg_hi:[1,0]
	v_pk_add_f32 v[0:1], v[18:19], 1.0 op_sel_hi:[1,0] neg_lo:[1,0] neg_hi:[1,0]
	v_pk_mul_f32 v[2:3], v[10:11], v[2:3]
	v_pk_add_f32 v[4:5], v[22:23], 1.0 op_sel_hi:[1,0] neg_lo:[1,0] neg_hi:[1,0]
	v_pk_mul_f32 v[0:1], v[8:9], v[0:1]
	v_pk_mul_f32 v[4:5], v[14:15], v[4:5]
	v_bfe_u32 v8, v7, 16, 1
	v_bfe_u32 v9, v6, 16, 1
	v_bfe_u32 v10, v3, 16, 1
	v_bfe_u32 v11, v2, 16, 1
	v_add3_u32 v11, v2, v11, s3
	v_add3_u32 v10, v3, v10, s3
	v_add3_u32 v2, v6, v9, s3
	v_add3_u32 v3, v7, v8, s3
	v_bfe_u32 v6, v0, 16, 1
	v_bfe_u32 v7, v1, 16, 1
	v_bfe_u32 v8, v4, 16, 1
	v_bfe_u32 v9, v5, 16, 1
	v_add3_u32 v5, v5, v9, s3
	v_add3_u32 v4, v4, v8, s3
	v_add3_u32 v1, v1, v7, s3
	v_add3_u32 v0, v0, v6, s3
	v_lshrrev_b32_e32 v0, 16, v0
	v_lshrrev_b32_e32 v1, 16, v1
	v_lshrrev_b32_e32 v4, 16, v4
	v_lshrrev_b32_e32 v5, 16, v5
	v_and_or_b32 v3, v3, s71, v5
	v_and_or_b32 v2, v2, s71, v4
	v_and_or_b32 v1, v10, s71, v1
	v_and_or_b32 v0, v11, s71, v0
	v_cndmask_b32_e64 v19, v126, v121, s[54:55]
	ds_write_b128 v164, v[0:3] offset:8192
	v_lshl_or_b32 v0, v19, 7, v119
	v_lshl_add_u32 v1, v0, 2, 0
	v_lshl_add_u32 v0, v0, 1, s18
	s_waitcnt lgkmcnt(0)
	s_barrier
	ds_read_b32 v173, v1 offset:40960
	ds_read_u16 v228, v0
	v_cndmask_b32_e64 v5, v142, v128, s[54:55]
	v_cndmask_b32_e64 v9, v154, v131, s[54:55]
	v_cndmask_b32_e64 v3, v155, v132, s[54:55]
	v_cndmask_b32_e64 v0, v139, v127, s[54:55]
	v_lshl_or_b32 v0, v0, 7, v119
	v_lshl_add_u32 v1, v0, 2, 0
	v_lshl_add_u32 v0, v0, 1, s18
	ds_read_b32 v229, v1 offset:40960
	ds_read_u16 v230, v0
	v_cndmask_b32_e64 v18, v157, v134, s[54:55]
	v_cndmask_b32_e64 v8, v158, v135, s[54:55]
	v_cndmask_b32_e64 v6, v159, v136, s[54:55]
	v_lshl_or_b32 v0, v5, 7, v119
	v_lshl_add_u32 v1, v0, 2, 0
	v_lshl_add_u32 v0, v0, 1, s18
	ds_read_b32 v231, v1 offset:40960
	ds_read_u16 v232, v0
	v_cndmask_b32_e64 v21, v161, v138, s[54:55]
	v_cndmask_b32_e64 v11, v163, v162, s[54:55]
	v_lshl_add_u32 v19, v19, 1, v186
	v_cndmask_b32_e64 v0, v152, v129, s[54:55]
	v_lshl_or_b32 v1, v0, 7, v119
	v_lshl_add_u32 v2, v1, 2, 0
	v_lshl_add_u32 v1, v1, 1, s18
	ds_read_b32 v233, v2 offset:40960
	ds_read_u16 v234, v1
	v_lshl_add_u32 v5, v5, 1, v186
	v_lshl_add_u32 v0, v0, 1, v186
	s_and_b64 s[0:1], s[54:55], exec
	v_lshl_or_b32 v1, v13, 7, v119
	v_lshl_add_u32 v2, v1, 2, 0
	v_lshl_add_u32 v1, v1, 1, s18
	ds_read_b32 v235, v2 offset:40960
	ds_read_u16 v236, v1
	s_cselect_b32 s56, s19, s20
	v_lshl_or_b32 v1, v9, 7, v119
	v_lshl_add_u32 v2, v1, 2, 0
	v_lshl_add_u32 v1, v1, 1, s18
	ds_read_b32 v237, v2 offset:40960
	ds_read_u16 v238, v1
	v_lshl_or_b32 v1, v3, 7, v119
	v_lshl_add_u32 v2, v1, 2, 0
	v_lshl_add_u32 v1, v1, 1, s18
	ds_read_b32 v239, v2 offset:40960
	ds_read_u16 v240, v1
	v_lshl_add_u32 v3, v3, 1, v186
	v_cndmask_b32_e64 v1, v156, v133, s[54:55]
	v_lshl_or_b32 v2, v1, 7, v119
	v_lshl_add_u32 v4, v2, 2, 0
	v_lshl_add_u32 v2, v2, 1, s18
	ds_read_b32 v241, v4 offset:40960
	ds_read_u16 v242, v2
	s_waitcnt lgkmcnt(0)
	v_add_f32_e32 v199, 0, v173
	v_lshlrev_b32_e32 v194, 16, v228
	v_add_f32_e32 v31, v199, v229
	v_lshlrev_b32_e32 v26, 16, v230
	v_add_f32_e32 v24, v31, v231
	v_lshlrev_b32_e32 v17, 16, v232
	v_add_f32_e32 v10, v24, v233
	v_lshlrev_b32_e32 v200, 16, v234
	v_add_f32_e32 v196, v10, v235
	v_lshlrev_b32_e32 v195, 16, v236
	v_add_f32_e32 v189, v196, v237
	v_lshlrev_b32_e32 v27, 16, v238
	v_add_f32_e32 v20, v189, v239
	v_lshlrev_b32_e32 v14, 16, v240
	v_add_f32_e32 v12, v20, v241
	v_lshlrev_b32_e32 v202, 16, v242
	v_lshl_add_u32 v1, v1, 1, v186
	v_lshl_or_b32 v2, v18, 7, v119
	v_lshl_add_u32 v4, v2, 2, 0
	v_lshl_add_u32 v2, v2, 1, s18
	ds_read_b32 v173, v4 offset:40960
	ds_read_u16 v228, v2
	v_lshl_or_b32 v2, v8, 7, v119
	v_lshl_add_u32 v4, v2, 2, 0
	v_lshl_add_u32 v2, v2, 1, s18
	ds_read_b32 v229, v4 offset:40960
	ds_read_u16 v230, v2
	v_lshl_or_b32 v2, v6, 7, v119
	v_lshl_add_u32 v4, v2, 2, 0
	v_lshl_add_u32 v2, v2, 1, s18
	ds_read_b32 v231, v4 offset:40960
	ds_read_u16 v232, v2
	v_cndmask_b32_e64 v2, v160, v137, s[54:55]
	v_lshl_or_b32 v4, v2, 7, v119
	v_lshl_add_u32 v7, v4, 2, 0
	v_lshl_add_u32 v4, v4, 1, s18
	ds_read_b32 v233, v7 offset:40960
	ds_read_u16 v234, v4
	v_lshl_or_b32 v4, v21, 7, v119
	v_lshl_add_u32 v7, v4, 2, 0
	v_lshl_add_u32 v4, v4, 1, s18
	ds_read_b32 v235, v7 offset:40960
	ds_read_u16 v236, v4
	v_lshl_or_b32 v4, v11, 7, v119
	v_lshl_add_u32 v7, v4, 2, 0
	ds_read_b32 v237, v7 offset:40960
	v_lshl_add_u32 v4, v4, 1, s18
	ds_read_u16 v238, v4
	v_cndmask_b32_e64 v7, v167, v166, s[54:55]
	v_lshl_or_b32 v4, v7, 7, v119
	v_lshl_add_u32 v22, v4, 2, 0
	v_lshl_add_u32 v4, v4, 1, s18
	ds_read_b32 v239, v22 offset:40960
	ds_read_u16 v240, v4
	v_cndmask_b32_e64 v4, v169, v168, s[54:55]
	v_lshl_or_b32 v174, v4, 7, v119
	v_lshl_add_u32 v23, v174, 2, 0
	ds_read_b32 v241, v23 offset:40960
	v_lshl_add_u32 v174, v174, 1, s18
	ds_read_u16 v174, v174
	s_waitcnt lgkmcnt(0)
	v_add_f32_e32 v197, v12, v173
	v_lshlrev_b32_e32 v191, 16, v228
	v_add_f32_e32 v188, v197, v229
	v_lshlrev_b32_e32 v28, 16, v230
	v_add_f32_e32 v25, v188, v231
	v_lshlrev_b32_e32 v15, 16, v232
	v_add_f32_e32 v16, v25, v233
	v_lshlrev_b32_e32 v29, 16, v234
	v_add_f32_e32 v201, v16, v235
	v_lshlrev_b32_e32 v192, 16, v236
	v_add_f32_e32 v193, v201, v237
	v_lshlrev_b32_e32 v190, 16, v238
	v_add_f32_e32 v30, v193, v239
	v_lshlrev_b32_e32 v22, 16, v240
	v_add_f32_e32 v23, v30, v241
	ds_write_b32 v185, v23 offset:36864
	s_waitcnt lgkmcnt(0)
	s_barrier
; #define LAS __attribute__((address_space(3)))
; __device__ __forceinline__ unsigned f2bf(float f) { unsigned u = __float_as_uint(f); return (u + 0x7fffu + ((u >> 16) & 1u)) >> 16; }
; __device__ __forceinline__ void hgrn_prefix(HgrnT& G, int k, int Is, const LAS float* tot) {
;     float r = 0.f, rt = 0.f;
; #pragma unroll
;     for (int i = 0; i < 4; ++i) { const float v = tot[i * 128 + k]; rt += v; if (i < Is) r += v; }
;     G.r = r; G.rtot = rt;
; }
; __device__ __forceinline__ void hgrn_a_item(const u16* P, const float* LBl0, const float* LBl1, float* ST, float* DT, int rc, int h, LAS unsigned char* L, int tid) {
;     ...
;         hgrn_prefix(G, k, Is, tot);
;         const int n = scan_index(dir, rc);
; #pragma unroll
;         for (int js = 0; js < 16; ++js) { const int t = dir ? 63 - (16 * Is + js) : 16 * Is + js;
;             Kd[k * 72 + t] = (u16)f2bf(G.kk[js] * __expf(G.rtot - G.r - G.bl[js])); }
;         if (Is == 0) DT[((size_t)(dir * NCH + n) * 4 + h) * 128 + k] = __expf(G.rtot);
	ds_read2st64_b32 v[204:205], v184 offset0:144 offset1:146
	v_lshlrev_b32_e32 v198, 16, v174
	s_waitcnt lgkmcnt(0)
	v_add_f32_e32 v174, 0, v204
	v_cndmask_b32_e64 v175, 0, v174, s[38:39]
	v_add_f32_e32 v174, v174, v205
	v_add_f32_e32 v181, v205, v175
	ds_read2st64_b32 v[204:205], v184 offset0:148 offset1:150
	v_cndmask_b32_e64 v175, v175, v181, s[40:41]
	s_waitcnt lgkmcnt(0)
	v_add_f32_e32 v181, v204, v175
	v_add_f32_e32 v174, v174, v204
	v_cndmask_b32_e64 v175, v175, v181, s[42:43]
	v_add_f32_e32 v203, v174, v205
	v_add_f32_e32 v174, v205, v175
	v_cndmask_b32_e64 v174, v175, v174, s[44:45]
	v_sub_f32_e32 v174, v203, v174
	v_sub_f32_e32 v175, v174, v199
	v_mul_f32_e32 v175, 0x3fb8aa3b, v175
	v_exp_f32_e32 v175, v175
	v_sub_f32_e32 v31, v174, v31
	v_mul_f32_e32 v31, 0x3fb8aa3b, v31
	v_exp_f32_e32 v31, v31
	v_mul_f32_e32 v175, v175, v194
	v_bfe_u32 v181, v175, 16, 1
	v_add3_u32 v175, v175, v181, s3
	v_mul_f32_e32 v26, v31, v26
	ds_write_b16_d16_hi v19, v175 offset:18432
	v_cndmask_b32_e64 v19, v187, v127, s[54:55]
	v_bfe_u32 v31, v26, 16, 1
	v_add3_u32 v26, v26, v31, s3
	v_lshl_add_u32 v19, v19, 1, v186
	ds_write_b16_d16_hi v19, v26 offset:18432
	v_sub_f32_e32 v19, v174, v24
	v_mul_f32_e32 v19, 0x3fb8aa3b, v19
	v_exp_f32_e32 v19, v19
	s_nop 0
	v_mul_f32_e32 v17, v19, v17
	v_bfe_u32 v19, v17, 16, 1
	v_add3_u32 v17, v17, v19, s3
	ds_write_b16_d16_hi v5, v17 offset:18432
	v_sub_f32_e32 v5, v174, v10
	v_mul_f32_e32 v5, 0x3fb8aa3b, v5
	v_exp_f32_e32 v5, v5
	s_nop 0
	v_mul_f32_e32 v5, v5, v200
	v_bfe_u32 v10, v5, 16, 1
	v_add3_u32 v5, v5, v10, s3
	ds_write_b16_d16_hi v0, v5 offset:18432
	v_sub_f32_e32 v0, v174, v196
	v_mul_f32_e32 v0, 0x3fb8aa3b, v0
	v_exp_f32_e32 v0, v0
	s_nop 0
	v_mul_f32_e32 v0, v0, v195
	v_bfe_u32 v5, v0, 16, 1
	v_add3_u32 v0, v0, v5, s3
	v_lshl_add_u32 v5, v13, 1, v186
	ds_write_b16_d16_hi v5, v0 offset:18432
	v_sub_f32_e32 v0, v174, v189
	v_mul_f32_e32 v0, 0x3fb8aa3b, v0
	v_exp_f32_e32 v0, v0
	s_nop 0
	v_mul_f32_e32 v0, v0, v27
	v_bfe_u32 v5, v0, 16, 1
	v_add3_u32 v0, v0, v5, s3
	v_lshl_add_u32 v5, v9, 1, v186
	ds_write_b16_d16_hi v5, v0 offset:18432
	v_sub_f32_e32 v0, v174, v20
	v_mul_f32_e32 v0, 0x3fb8aa3b, v0
	v_exp_f32_e32 v0, v0
	s_nop 0
	v_mul_f32_e32 v0, v0, v14
	v_bfe_u32 v5, v0, 16, 1
	v_add3_u32 v0, v0, v5, s3
	ds_write_b16_d16_hi v3, v0 offset:18432
	v_sub_f32_e32 v0, v174, v12
	v_mul_f32_e32 v0, 0x3fb8aa3b, v0
	v_exp_f32_e32 v0, v0
	s_nop 0
	v_mul_f32_e32 v0, v0, v202
	v_bfe_u32 v3, v0, 16, 1
	v_add3_u32 v0, v0, v3, s3
	ds_write_b16_d16_hi v1, v0 offset:18432
	v_sub_f32_e32 v0, v174, v197
	v_mul_f32_e32 v0, 0x3fb8aa3b, v0
	v_exp_f32_e32 v0, v0
	s_nop 0
	v_mul_f32_e32 v0, v0, v191
	v_bfe_u32 v1, v0, 16, 1
	v_add3_u32 v0, v0, v1, s3
	v_lshl_add_u32 v1, v18, 1, v186
	ds_write_b16_d16_hi v1, v0 offset:18432
	v_sub_f32_e32 v0, v174, v188
	v_mul_f32_e32 v0, 0x3fb8aa3b, v0
	v_exp_f32_e32 v0, v0
	s_nop 0
	v_mul_f32_e32 v0, v0, v28
	v_bfe_u32 v1, v0, 16, 1
	v_add3_u32 v0, v0, v1, s3
	v_lshl_add_u32 v1, v8, 1, v186
	ds_write_b16_d16_hi v1, v0 offset:18432
	v_sub_f32_e32 v0, v174, v25
	v_mul_f32_e32 v0, 0x3fb8aa3b, v0
	v_exp_f32_e32 v0, v0
	s_nop 0
	v_mul_f32_e32 v0, v0, v15
	v_bfe_u32 v1, v0, 16, 1
	v_add3_u32 v0, v0, v1, s3
	v_lshl_add_u32 v1, v6, 1, v186
	ds_write_b16_d16_hi v1, v0 offset:18432
	v_sub_f32_e32 v0, v174, v16
	v_mul_f32_e32 v0, 0x3fb8aa3b, v0
	v_exp_f32_e32 v0, v0
	s_nop 0
	v_mul_f32_e32 v0, v0, v29
	v_bfe_u32 v1, v0, 16, 1
	v_add3_u32 v0, v0, v1, s3
	v_lshl_add_u32 v1, v2, 1, v186
	ds_write_b16_d16_hi v1, v0 offset:18432
	v_sub_f32_e32 v0, v174, v201
	v_mul_f32_e32 v0, 0x3fb8aa3b, v0
	v_exp_f32_e32 v0, v0
	s_nop 0
	v_mul_f32_e32 v0, v0, v192
	v_bfe_u32 v1, v0, 16, 1
	v_add3_u32 v0, v0, v1, s3
	v_lshl_add_u32 v1, v21, 1, v186
	ds_write_b16_d16_hi v1, v0 offset:18432
	v_sub_f32_e32 v0, v174, v193
	v_mul_f32_e32 v0, 0x3fb8aa3b, v0
	v_exp_f32_e32 v0, v0
	s_nop 0
	v_mul_f32_e32 v0, v0, v190
	v_bfe_u32 v1, v0, 16, 1
	v_add3_u32 v0, v0, v1, s3
	v_lshl_add_u32 v1, v11, 1, v186
	ds_write_b16_d16_hi v1, v0 offset:18432
	v_sub_f32_e32 v0, v174, v30
	v_mul_f32_e32 v0, 0x3fb8aa3b, v0
	v_exp_f32_e32 v0, v0
	s_nop 0
	v_mul_f32_e32 v0, v0, v22
	v_bfe_u32 v1, v0, 16, 1
	v_add3_u32 v0, v0, v1, s3
	v_lshl_add_u32 v1, v7, 1, v186
	ds_write_b16_d16_hi v1, v0 offset:18432
	v_sub_f32_e32 v0, v174, v23
	v_mul_f32_e32 v0, 0x3fb8aa3b, v0
	v_exp_f32_e32 v0, v0
	s_nop 0
	v_mul_f32_e32 v0, v0, v198
	v_bfe_u32 v1, v0, 16, 1
	v_add3_u32 v0, v0, v1, s3
	v_lshl_add_u32 v1, v4, 1, v186
	ds_write_b16_d16_hi v1, v0 offset:18432
	s_and_saveexec_b64 s[0:1], s[46:47]
	s_xor_b64 s[0:1], exec, s[0:1]
	s_add_i32 s22, s56, s21
	s_ashr_i32 s23, s22, 31
	s_or_saveexec_b64 s[0:1], s[0:1]
	v_mov_b64_e32 v[16:17], s[22:23]
	s_xor_b64 exec, exec, s[0:1]
	s_cbranch_execz .LBB0_342
	v_mul_f32_e32 v0, 0x3fb8aa3b, v203
	v_exp_f32_e32 v2, v0
	s_add_i32 s22, s56, s21
	s_ashr_i32 s23, s22, 31
	s_lshl_b64 s[56:57], s[22:23], 11
	v_lshl_add_u64 v[0:1], v[66:67], 0, s[56:57]
	v_mov_b64_e32 v[16:17], s[22:23]
	global_store_dword v[0:1], v2, off
	s_branch .LBB0_342
